# v18: bias-table fill overlapped with the base table fill; second unit of a pair skips both fills
# baseline (speedup 1.0000x reference)
.LBB0_626:
	v_mov_b32_e32 v2, v200
	s_waitcnt vmcnt(0) lgkmcnt(0)
	v_cmp_gt_i32_e32 vcc, s63, v2
	s_barrier
	s_cmp_eq_u64 s[2:3], 0
	s_cbranch_scc1 .Lnsa2_skipfill
	v_add_u32_e32 v206, 0, v200
	v_min_u32_e32 v206, 1407, v206
	v_cmp_lt_u32_e32 vcc, 703, v206
	v_mov_b32_e32 v213, 0
	s_nop 0
	v_cndmask_b32_e64 v207, 0, 1, vcc
	v_mul_u32_u24_e32 v208, 704, v207
	v_sub_u32_e32 v208, v206, v208
	v_subrev_u32_e32 v209, 96, v208
	v_max_i32_e32 v210, 0, v209
	v_min_i32_e32 v210, 0x80, v210
	v_lshlrev_b32_e32 v210, 2, v210
	v_add_u32_e32 v210, 0x20004, v210
	ds_read_b32 v210, v210
	v_mul_u32_u24_e32 v211, 0xb00, v207
	v_lshl_add_u32 v211, v208, 2, v211
	v_add_u32_e32 v211, 0x1d000, v211
	v_add_u32_e32 v218, 512, v200
	v_min_u32_e32 v218, 1407, v218
	v_cmp_lt_u32_e32 vcc, 703, v218
	v_mov_b32_e32 v225, 0
	s_nop 0
	v_cndmask_b32_e64 v219, 0, 1, vcc
	v_mul_u32_u24_e32 v220, 704, v219
	v_sub_u32_e32 v220, v218, v220
	v_subrev_u32_e32 v221, 96, v220
	v_max_i32_e32 v222, 0, v221
	v_min_i32_e32 v222, 0x80, v222
	v_lshlrev_b32_e32 v222, 2, v222
	v_add_u32_e32 v222, 0x20004, v222
	ds_read_b32 v222, v222
	v_mul_u32_u24_e32 v223, 0xb00, v219
	v_lshl_add_u32 v223, v220, 2, v223
	v_add_u32_e32 v223, 0x1d000, v223
	v_add_u32_e32 v230, 1024, v200
	v_min_u32_e32 v230, 1407, v230
	v_cmp_lt_u32_e32 vcc, 703, v230
	v_mov_b32_e32 v237, 0
	s_nop 0
	v_cndmask_b32_e64 v231, 0, 1, vcc
	v_mul_u32_u24_e32 v232, 704, v231
	v_sub_u32_e32 v232, v230, v232
	v_subrev_u32_e32 v233, 96, v232
	v_max_i32_e32 v234, 0, v233
	v_min_i32_e32 v234, 0x80, v234
	v_lshlrev_b32_e32 v234, 2, v234
	v_add_u32_e32 v234, 0x20004, v234
	ds_read_b32 v234, v234
	v_mul_u32_u24_e32 v235, 0xb00, v231
	v_lshl_add_u32 v235, v232, 2, v235
	v_add_u32_e32 v235, 0x1d000, v235
	s_waitcnt lgkmcnt(0)
	v_mul_lo_u32 v210, v210, 12
	v_add3_u32 v212, v210, v207, s81
	v_ashrrev_i32_e32 v213, 31, v212
	v_lshl_add_u64 v[212:213], v[212:213], 2, s[56:57]
	global_load_dword v214, v[212:213], off
	v_mul_lo_u32 v222, v222, 12
	v_add3_u32 v224, v222, v219, s81
	v_ashrrev_i32_e32 v225, 31, v224
	v_lshl_add_u64 v[224:225], v[224:225], 2, s[56:57]
	global_load_dword v226, v[224:225], off
	v_mul_lo_u32 v234, v234, 12
	v_add3_u32 v236, v234, v231, s81
	v_ashrrev_i32_e32 v237, 31, v236
	v_lshl_add_u64 v[236:237], v[236:237], 2, s[56:57]
	global_load_dword v238, v[236:237], off
	v_cmp_gt_i32_e32 vcc, s63, v2
	s_and_saveexec_b64 s[4:5], vcc
	s_cbranch_execz .LBB0_631
	v_lshl_add_u32 v0, v2, 2, 0
	s_mov_b64 s[6:7], 0
	v_mov_b32_e32 v3, v2
	s_branch .LBB0_629

.LBB0_631:
	s_or_b64 exec, exec, s[4:5]
	v_mov_b32_e32 v205, 0xf149f2ca
	v_mov_b32_e32 v204, 0x1ff
	s_waitcnt vmcnt(0)
	v_cmp_gt_u32_e32 vcc, v209, v204
	v_mul_f32_e32 v214, 0x41000000, v214
	s_nop 0
	v_cndmask_b32_e32 v214, v214, v205, vcc
	ds_write_b32 v211, v214
	v_cmp_gt_u32_e32 vcc, v221, v204
	v_mul_f32_e32 v226, 0x41000000, v226
	s_nop 0
	v_cndmask_b32_e32 v226, v226, v205, vcc
	ds_write_b32 v223, v226
	v_cmp_gt_u32_e32 vcc, v233, v204
	v_mul_f32_e32 v238, 0x41000000, v238
	s_nop 0
	v_cndmask_b32_e32 v238, v238, v205, vcc
	ds_write_b32 v235, v238

.LBB0_1286:
	v_mov_b32_e32 v78, v200
	s_waitcnt vmcnt(0) lgkmcnt(0)
	v_cmp_gt_i32_e32 vcc, s80, v78
	s_barrier
	s_cmp_eq_u64 s[2:3], 0
	s_cbranch_scc1 .Lmoba_skipfill
	v_lshrrev_b32_e32 v236, 6, v200
	v_mul_u32_u24_e32 v236, 0xc00, v236
	v_and_b32_e32 v237, 63, v200
	v_lshl_add_u32 v236, v237, 2, v236
	v_mov_b32_e32 v237, 0
	v_lshl_add_u64 v[236:237], v[236:237], 0, s[50:51]
	v_lshl_add_u64 v[236:237], v[236:237], 0, s[34:35]
	global_load_dword v238, v[236:237], off
	v_add_u32_e32 v206, 0, v200
	v_min_u32_e32 v206, 703, v206
	v_cmp_lt_u32_e32 vcc, 703, v206
	v_mov_b32_e32 v213, 0
	s_nop 0
	v_cndmask_b32_e64 v207, 0, 1, vcc
	v_mul_u32_u24_e32 v208, 704, v207
	v_sub_u32_e32 v208, v206, v208
	v_subrev_u32_e32 v209, 96, v208
	v_max_i32_e32 v210, 0, v209
	v_min_i32_e32 v210, 0x80, v210
	v_lshlrev_b32_e32 v210, 2, v210
	v_add_u32_e32 v210, 0x20004, v210
	ds_read_b32 v210, v210
	v_mul_u32_u24_e32 v211, 0xb00, v207
	v_lshl_add_u32 v211, v208, 2, v211
	v_add_u32_e32 v211, 0x1d000, v211
	v_add_u32_e32 v218, 512, v200
	v_min_u32_e32 v218, 703, v218
	v_cmp_lt_u32_e32 vcc, 703, v218
	v_mov_b32_e32 v225, 0
	s_nop 0
	v_cndmask_b32_e64 v219, 0, 1, vcc
	v_mul_u32_u24_e32 v220, 704, v219
	v_sub_u32_e32 v220, v218, v220
	v_subrev_u32_e32 v221, 96, v220
	v_max_i32_e32 v222, 0, v221
	v_min_i32_e32 v222, 0x80, v222
	v_lshlrev_b32_e32 v222, 2, v222
	v_add_u32_e32 v222, 0x20004, v222
	ds_read_b32 v222, v222
	v_mul_u32_u24_e32 v223, 0xb00, v219
	v_lshl_add_u32 v223, v220, 2, v223
	v_add_u32_e32 v223, 0x1d000, v223
	s_waitcnt lgkmcnt(0)
	v_mul_lo_u32 v210, v210, 12
	v_add3_u32 v212, v210, v207, s94
	v_ashrrev_i32_e32 v213, 31, v212
	v_lshl_add_u64 v[212:213], v[212:213], 2, s[56:57]
	global_load_dword v214, v[212:213], off
	v_mul_lo_u32 v222, v222, 12
	v_add3_u32 v224, v222, v219, s94
	v_ashrrev_i32_e32 v225, 31, v224
	v_lshl_add_u64 v[224:225], v[224:225], 2, s[56:57]
	global_load_dword v226, v[224:225], off
	v_cmp_gt_i32_e32 vcc, s80, v78
	s_and_saveexec_b64 s[4:5], vcc
	s_cbranch_execz .LBB0_1291
	v_lshl_add_u32 v0, v78, 2, 0
	s_mov_b64 s[6:7], 0
	v_mov_b32_e32 v1, v78
	s_branch .LBB0_1289

.LBB0_1291:
	s_or_b64 exec, exec, s[4:5]
	v_mov_b32_e32 v205, 0xf149f2ca
	v_mov_b32_e32 v204, 0x1ff
	s_waitcnt vmcnt(0)
	v_cmp_gt_u32_e32 vcc, v209, v204
	v_mul_f32_e32 v214, 0x41000000, v214
	s_nop 0
	v_cndmask_b32_e32 v214, v214, v205, vcc
	ds_write_b32 v211, v214
	v_cmp_gt_u32_e32 vcc, v221, v204
	v_mul_f32_e32 v226, 0x41000000, v226
	s_nop 0
	v_cndmask_b32_e32 v226, v226, v205, vcc
	ds_write_b32 v223, v226
	v_lshlrev_b32_e32 v239, 2, v200
	v_add_u32_e32 v239, 0x1e000, v239
	ds_write_b32 v239, v238
	s_waitcnt lgkmcnt(0)
	s_barrier
